# scan waves: y reduced in batches of 16 (v2 body) + loader waves keep 9 LoRA fragments in registers, QA ks=1 loaded early
# speedup vs baseline: 1.0206x; 1.0041x over previous
; #define LAS __attribute__((address_space(3)))
; __device__ __forceinline__ void phase_scan(const Params& p, LAS unsigned char* lds) {
;     ...
;         const int pw_ = wave & 3, s_sub = lane >> 3, c8 = (lane & 7) * 8, s_l = 8 * pw_ + s_sub;
;         h16x8 mu_r8, mu_k8, mu_v8, mu_w8, mu_a8; f32x2 w0r[4], a0r[4], kkr[4], kar[4], omk[4], rkr[4];
; #pragma unroll
;         for (int e = 0; e < 8; ++e) { mu_r8[e] = (h16)mu[64 * h + c8 + e]; mu_k8[e] = (h16)mu[1024 + 64 * h + c8 + e]; mu_v8[e] = (h16)mu[2048 + 64 * h + c8 + e]; mu_w8[e] = (h16)mu[3072 + c8 + e]; mu_a8[e] = (h16)mu[3136 + c8 + e];
;             w0r[e >> 1][e & 1] = w0[c8 + e]; a0r[e >> 1][e & 1] = a0[c8 + e]; kkr[e >> 1][e & 1] = kkw[c8 + e]; kar[e >> 1][e & 1] = kaw[c8 + e]; omk[e >> 1][e & 1] = 1.f - kaw[c8 + e]; rkr[e >> 1][e & 1] = rkw[c8 + e]; }
;         f32x2 S01 = {0.f, 0.f}, S23 = {0.f, 0.f};
;         const int srow = 4 * (wave & 3) + (lane >> 4), j0 = 4 * (lane & 15);
;         const h16x8 z8 = {0, 0, 0, 0, 0, 0, 0, 0};
;         h16x8 pr, pk, pv, pw, pa, qr_, qk_, qv_, qw_, qa_;
;         const h16 *pcA, *pcB, *ppA, *ppB;
;         { const int t0_ = dir ? (SEQ - 1 - s_l) : s_l; pcA = PC + (size_t)(b * SEQ + t0_) * 3200 + c8 + 64 * h; pcB = pcA + 2048 - 64 * h;
;           const long po_ = (s_l > 0) ? (dir ? 3200 : -3200) : 0; ppA = pcA + po_; ppB = pcB + po_; }
;         const long cstride_ = dir ? -32 * 3200 : 32 * 3200;
;     ...
;         if (wave >= 4) { SCAN_LOAD_RAW(); if (s_l == 0) { qr_ = z8; qk_ = z8; qv_ = z8; qw_ = z8; qa_ = z8; } }
;         __syncthreads();
;     ...
;                     for (int ks = 0; ks < 2; ++ks) {
;                         const h16x8 atw = *(const LAS h16x8*)(TWp + (lane & 7) * 72 + 32 * ks + 8 * (lane >> 4));
;                         const h16x8 aqa = *(const LAS h16x8*)(QAp + (lane & 7) * 72 + 32 * ks + 8 * (lane >> 4));
; #pragma unroll
;                         for (int ct = 0; ct < 4; ++ct) {
;                             const h16x8 bw = *(const LAS h16x8*)(w2T + (16 * ct + (lane & 15)) * 72 + 32 * ks + 8 * (lane >> 4));
;                             const h16x8 ba = *(const LAS h16x8*)(a2T + (16 * ct + (lane & 15)) * 72 + 32 * ks + 8 * (lane >> 4));
.LBB0_601:
	s_or_b64 exec, exec, s[10:11]
	s_waitcnt vmcnt(16)
	v_cvt_f16_f32_e32 v64, v64
	s_waitcnt vmcnt(13)
	v_cvt_f16_f32_e32 v68, v94
	v_cvt_f16_f32_e32 v0, v60
	s_waitcnt vmcnt(11)
	v_cvt_f16_f32_e32 v69, v98
	v_cvt_f16_f32_e32 v3, v90
	v_cvt_pk_f16_f32 v65, v65, v66
	v_cvt_pk_f16_f32 v90, v95, v96
	v_cvt_pk_f16_f32 v61, v61, v62
	v_pack_b32_f16 v62, v64, v65
	v_pack_b32_f16 v64, v68, v90
	v_cvt_pk_f16_f32 v68, v99, v100
	s_lshl_b64 s[48:49], s[12:13], 25
	s_lshl_b64 s[10:11], s[12:13], 20
	s_bfe_u32 s15, s78, 0x20003
	v_pack_b32_f16 v2, v0, v61
	v_cvt_pk_f16_f32 v0, v91, v92
	v_pack_b32_f16 v66, v69, v68
	v_cvt_pk_f16_f32 v69, v63, v74
	v_cvt_pk_f16_f32 v74, v93, v82
	s_waitcnt vmcnt(10)
	v_cvt_pk_f16_f32 v78, v101, v78
	v_cvt_pk_f16_f32 v75, v75, v76
	v_pack_b32_f16 v60, v3, v0
	v_alignbit_b32 v3, v69, v61, 16
	v_alignbit_b32 v61, v74, v0, 16
	v_cvt_pk_f16_f32 v0, v67, v70
	v_alignbit_b32 v67, v78, v68, 16
	v_alignbit_b32 v68, v75, v69, 16
	v_cvt_f16_f32_e32 v69, v77
	s_add_u32 s48, s68, s48
	s_addc_u32 s49, s69, s49
	s_add_u32 s34, s31, s10
	s_addc_u32 s35, s33, s11
	v_alignbit_b32 v69, v69, v75, 16
	v_cvt_f16_f32_e32 v75, v89
	s_add_u32 s54, s48, s20
	v_cvt_pk_f16_f32 v77, v79, v80
	s_addc_u32 s55, s49, 0
	s_lshl_b32 s14, s14, 2
	v_cvt_pk_f16_f32 v83, v83, v84
	v_cvt_pk_f16_f32 v84, v71, v72
	v_alignbit_b32 v76, v77, v78, 16
	v_cvt_f16_f32_e32 v71, v85
	v_cvt_f16_f32_e32 v73, v73
	v_cvt_f16_f32_e32 v78, v81
	s_add_u32 s52, s34, s14
	v_alignbit_b32 v63, v0, v65, 16
	v_cvt_pk_f16_f32 v82, v97, v86
	v_alignbit_b32 v72, v84, v0, 16
	v_cvt_pk_f16_f32 v0, v87, v88
	s_addc_u32 s53, s35, 0
	s_lshl_b32 s80, s15, 4
	s_lshl_b32 s14, s15, 5
	v_alignbit_b32 v70, v83, v74, 16
	v_alignbit_b32 v74, v0, v82, 16
	v_alignbit_b32 v75, v75, v0, 16
	v_or_b32_e32 v0, s15, v133
	s_add_u32 s14, s54, s14
	v_cmp_eq_u32_e64 s[10:11], s15, v176
	v_cmp_eq_u32_e64 s[12:13], 0, v0
	s_addc_u32 s15, s55, 0
	v_mov_b32_e32 v143, v1
	v_mov_b32_e32 v0, v1
	s_waitcnt vmcnt(2)
	v_pk_add_f32 v[154:155], v[48:49], 1.0 op_sel_hi:[1,0] neg_lo:[1,0] neg_hi:[1,0]
	v_pk_add_f32 v[156:157], v[50:51], 1.0 op_sel_hi:[1,0] neg_lo:[1,0] neg_hi:[1,0]
	v_alignbit_b32 v65, v82, v90, 16
	v_pk_add_f32 v[158:159], v[44:45], 1.0 op_sel_hi:[1,0] neg_lo:[1,0] neg_hi:[1,0]
	v_alignbit_b32 v71, v71, v83, 16
	v_alignbit_b32 v73, v73, v84, 16
	v_alignbit_b32 v77, v78, v77, 16
	v_pk_add_f32 v[160:161], v[46:47], 1.0 op_sel_hi:[1,0] neg_lo:[1,0] neg_hi:[1,0]
	s_waitcnt lgkmcnt(0)
	s_barrier
	v_lshl_add_u64 v[162:163], s[14:15], 0, v[142:143]
	s_mov_b32 s81, -1
	s_movk_i32 s82, 0xfc00
	v_mov_b32_e32 v143, v191
	v_mov_b32_e32 v145, v169
	v_mov_b64_e32 v[166:167], v[0:1]
	v_mov_b64_e32 v[164:165], v[0:1]
	s_cmp_eq_u64 s[0:1], 0
	s_cbranch_scc1 .Lhoist_skip
	ds_read_b128 v[132:135], v183 offset:64
	ds_read_b128 v[136:139], v183 offset:9280
	ds_read_b128 v[164:167], v183 offset:2368
	ds_read_b128 v[184:187], v183 offset:11584
	ds_read_b128 v[188:191], v183 offset:4672
	ds_read_b128 v[192:195], v183 offset:6976
	ds_read_b128 v[196:199], v183 offset:13888
	ds_read_b128 v[246:249], v183 offset:16192
	ds_read_b128 v[250:253], v183 offset:6912
	s_waitcnt lgkmcnt(0)

; #define LAS __attribute__((address_space(3)))
; #define LDS_WAIT() asm volatile("s_waitcnt lgkmcnt(0)" ::: "memory")
; __device__ __forceinline__ void phase_scan(const Params& p, LAS unsigned char* lds) {
;     ...
;                     LDS_WAIT();
;                     f32x4 accw[4], acca[4];
; #pragma unroll
;                     for (int ct = 0; ct < 4; ++ct) { accw[ct] = (f32x4){0.f, 0.f, 0.f, 0.f}; acca[ct] = (f32x4){0.f, 0.f, 0.f, 0.f}; }
; #pragma unroll
;                     for (int ks = 0; ks < 2; ++ks) {
;                         const h16x8 atw = *(const LAS h16x8*)(TWp + (lane & 7) * 72 + 32 * ks + 8 * (lane >> 4));
;                         const h16x8 aqa = *(const LAS h16x8*)(QAp + (lane & 7) * 72 + 32 * ks + 8 * (lane >> 4));
; #pragma unroll
;                         for (int ct = 0; ct < 4; ++ct) {
;                             const h16x8 bw = *(const LAS h16x8*)(w2T + (16 * ct + (lane & 15)) * 72 + 32 * ks + 8 * (lane >> 4));
;                             const h16x8 ba = *(const LAS h16x8*)(a2T + (16 * ct + (lane & 15)) * 72 + 32 * ks + 8 * (lane >> 4));
;                             accw[ct] = __builtin_amdgcn_mfma_f32_16x16x32_f16(atw, bw, accw[ct], 0, 0, 0);
;                             acca[ct] = __builtin_amdgcn_mfma_f32_16x16x32_f16(aqa, ba, acca[ct], 0, 0, 0);
;                         }
;                     }
;                     LDS_WAIT();
;                     { LAS float* Zd = (LAS float*)priv + (lane >> 5) * 512 + (4 * ((lane >> 4) & 1)) * 64 + (lane & 15);
; #pragma unroll
;                       for (int ct = 0; ct < 4; ++ct)
; #pragma unroll
;                           for (int r = 0; r < 4; ++r) Zd[r * 64 + 16 * ct] = (lane < 32) ? accw[ct][r] : acca[ct][r]; }
;                     LDS_WAIT();
;                     const LAS float* Zw = (const LAS float*)priv + s_sub * 64 + c8; const LAS float* Za = Zw + 512;
;                     const f32x4 zw0 = *(const LAS f32x4*)Zw, zw1 = *(const LAS f32x4*)(Zw + 4), za0 = *(const LAS f32x4*)Za, za1 = *(const LAS f32x4*)(Za + 4);
.LBB0_610:
	s_waitcnt lgkmcnt(0)
	v_pk_fma_f16 v222, v95, s14, v99
	v_pk_fma_f16 v218, v96, s14, v100
	v_pk_fma_f16 v219, v97, s14, v101
	ds_read_b128 v[126:129], v173 offset:18432
	ds_read_b128 v[202:205], v173 offset:19584
	ds_read_b128 v[206:209], v183
	ds_read_b128 v[210:213], v183 offset:9216
	v_pk_fma_f16 v0, v94, s14, v98
	ds_read_b128 v[214:217], v183 offset:2304
	ds_read_b128 v[98:101], v183 offset:11520
	v_pk_fma_f16 v242, v69, v219, v97
	v_pk_fma_f16 v238, v68, v218, v96
	ds_read_b128 v[218:221], v183 offset:4608
	v_pk_fma_f16 v239, v3, v222, v95
	ds_read_b128 v[222:225], v183 offset:13824
	ds_read_b128 v[230:233], v183 offset:16128
	ds_read_b128 v[234:237], v173 offset:18496
	ds_read_b128 v[226:229], v173 offset:19648
	s_waitcnt lgkmcnt(8)
	v_mfma_f32_16x16x32_f16 v[206:209], v[126:129], v[206:209], 0
	v_pk_fma_f16 v0, v2, v0, v94
	v_pk_fma_f16 v94, v86, s14, v90
	v_pk_fma_f16 v95, v87, s14, v91
	s_waitcnt lgkmcnt(7)
	v_mfma_f32_16x16x32_f16 v[210:213], v[202:205], v[210:213], 0
	v_pk_fma_f16 v240, v61, v95, v87
	v_cvt_f32_f16_sdwa v87, v0 dst_sel:DWORD dst_unused:UNUSED_PAD src0_sel:WORD_1
	s_bitcmp1_b32 s81, 0
	s_waitcnt lgkmcnt(6)
	v_mfma_f32_16x16x32_f16 v[214:217], v[126:129], v[214:217], 0
	s_cselect_b32 s15, 0, 0xa800
	s_add_i32 s15, s15, 0
	s_waitcnt lgkmcnt(5)
	v_mfma_f32_16x16x32_f16 v[96:99], v[202:205], v[98:101], 0
	v_pk_fma_f16 v100, v88, s14, v92
	v_pk_fma_f16 v101, v89, s14, v93
	v_pk_fma_f16 v244, v70, v100, v88
	s_waitcnt lgkmcnt(4)
	v_mfma_f32_16x16x32_f16 v[218:221], v[126:129], v[218:221], 0
	v_pk_fma_f16 v243, v71, v101, v89
	v_pk_fma_f16 v101, v60, v94, v86
	v_cvt_f32_f16_e32 v86, v0
	s_waitcnt lgkmcnt(3)
	v_mfma_f32_16x16x32_f16 v[222:225], v[202:205], v[222:225], 0
	v_cvt_f32_f16_e32 v100, v101
	v_cvt_f32_f16_sdwa v101, v101 dst_sel:DWORD dst_unused:UNUSED_PAD src0_sel:WORD_1
	v_mfma_f32_16x16x32_f16 v[126:129], v[126:129], v[250:253], 0
	s_waitcnt lgkmcnt(2)
	v_mfma_f32_16x16x32_f16 v[202:205], v[202:205], v[230:233], 0
	s_waitcnt lgkmcnt(1)
	v_mfma_f32_16x16x32_f16 v[206:209], v[234:237], v[132:135], v[206:209]
	s_waitcnt lgkmcnt(0)
	v_mfma_f32_16x16x32_f16 v[210:213], v[226:229], v[136:139], v[210:213]
	v_mfma_f32_16x16x32_f16 v[214:217], v[234:237], v[164:167], v[214:217]
	v_cvt_f32_f16_e32 v88, v239
	v_cvt_f32_f16_sdwa v89, v239 dst_sel:DWORD dst_unused:UNUSED_PAD src0_sel:WORD_1
	s_nop 2
	s_nop 1
	v_cndmask_b32_e64 v0, v210, v206, s[4:5]
	s_waitcnt lgkmcnt(0)
	v_mfma_f32_16x16x32_f16 v[218:221], v[234:237], v[188:191], v[218:221]
	v_cndmask_b32_e64 v206, v212, v208, s[4:5]
	v_add_u32_e32 v208, 0x4800, v174
	v_mfma_f32_16x16x32_f16 v[96:99], v[226:229], v[184:187], v[96:99]
	v_cvt_f32_f16_e32 v94, v240
	v_cvt_f32_f16_sdwa v95, v240 dst_sel:DWORD dst_unused:UNUSED_PAD src0_sel:WORD_1
	s_waitcnt lgkmcnt(0)
	v_mfma_f32_16x16x32_f16 v[222:225], v[226:229], v[196:199], v[222:225]
	v_cvt_f32_f16_e32 v90, v238
	v_cvt_f32_f16_sdwa v91, v238 dst_sel:DWORD dst_unused:UNUSED_PAD src0_sel:WORD_1
	v_mfma_f32_16x16x32_f16 v[126:129], v[234:237], v[192:195], v[126:129]
	s_nop 0
	v_cndmask_b32_e64 v96, v96, v214, s[4:5]
	s_waitcnt lgkmcnt(0)
	v_cndmask_b32_e64 v93, v211, v207, s[4:5]
	s_waitcnt lgkmcnt(0)
	v_mfma_f32_16x16x32_f16 v[202:205], v[226:229], v[246:249], v[202:205]
	ds_write2_b32 v208, v0, v96 offset1:16
	v_cndmask_b32_e64 v0, v97, v215, s[4:5]
	ds_write2_b32 v208, v93, v0 offset0:64 offset1:80
	v_cndmask_b32_e64 v0, v98, v216, s[4:5]
	v_cndmask_b32_e64 v207, v213, v209, s[4:5]
	ds_write2_b32 v208, v206, v0 offset0:128 offset1:144
	v_cndmask_b32_e64 v0, v99, v217, s[4:5]
	ds_write2_b32 v208, v207, v0 offset0:192 offset1:208
	v_cndmask_b32_e64 v0, v222, v218, s[4:5]
	v_cndmask_b32_e64 v98, v202, v126, s[4:5]
	v_cndmask_b32_e64 v93, v223, v219, s[4:5]
	ds_write2_b32 v208, v0, v98 offset0:32 offset1:48
	v_cndmask_b32_e64 v0, v203, v127, s[4:5]
	v_cndmask_b32_e64 v96, v224, v220, s[4:5]
	ds_write2_b32 v208, v93, v0 offset0:96 offset1:112
	v_cndmask_b32_e64 v0, v204, v128, s[4:5]
	v_cndmask_b32_e64 v97, v225, v221, s[4:5]
	ds_write2_b32 v208, v96, v0 offset0:160 offset1:176
	v_cndmask_b32_e64 v0, v205, v129, s[4:5]
	ds_write2_b32 v208, v97, v0 offset0:224 offset1:240
	s_waitcnt lgkmcnt(0)
	ds_read_b128 v[126:129], v200 offset:20480
	ds_read_b128 v[206:209], v200 offset:20496
	v_pk_mul_f32 v[212:213], v[40:41], v[100:101]
	v_pk_mul_f32 v[218:219], v[42:43], v[94:95]
	ds_read_b128 v[96:99], v200 offset:18432
	ds_read_b128 v[202:205], v200 offset:18448
	s_waitcnt lgkmcnt(3)
	v_pk_add_f32 v[126:127], v[32:33], v[126:127]
	s_waitcnt lgkmcnt(2)
	v_pk_add_f32 v[208:209], v[30:31], v[208:209]
	v_pk_mul_f32 v[126:127], v[126:127], s[36:37] op_sel_hi:[1,0]
	v_cvt_f32_f16_e32 v230, v244
	v_exp_f32_e32 v126, v126
	v_exp_f32_e32 v127, v127
	v_cvt_f32_f16_sdwa v231, v244 dst_sel:DWORD dst_unused:UNUSED_PAD src0_sel:WORD_1
	v_pk_mul_f32 v[208:209], v[208:209], s[36:37] op_sel_hi:[1,0]
	v_cvt_f32_f16_e32 v210, v243
	v_pk_add_f32 v[126:127], v[126:127], 1.0 op_sel_hi:[1,0]
	v_exp_f32_e32 v208, v208
	v_rcp_f32_e32 v214, v126
	v_rcp_f32_e32 v215, v127
	v_exp_f32_e32 v209, v209
	v_cvt_f32_f16_sdwa v211, v243 dst_sel:DWORD dst_unused:UNUSED_PAD src0_sel:WORD_1
	s_waitcnt lgkmcnt(1)
; #define LAS __attribute__((address_space(3)))
; __device__ __forceinline__ void phase_scan(const Params& p, LAS unsigned char* lds) {
;     ...
;                     f32x2 kk[4], av_[4], kp[4], dec[4], kn2 = {0.f, 0.f}, sb2 = {0.f, 0.f};
; #pragma unroll
;                     for (int pi = 0; pi < 4; ++pi) {
;                         const f32x2 zw = (pi < 2 ? (f32x2){zw0[2 * pi], zw0[2 * pi + 1]} : (f32x2){zw1[2 * pi - 4], zw1[2 * pi - 3]}) + w0r[pi];
;                         const f32x2 za = (pi < 2 ? (f32x2){za0[2 * pi], za0[2 * pi + 1]} : (f32x2){za1[2 * pi - 4], za1[2 * pi - 3]}) + a0r[pi];
;                         const f32x2 tw_ = zw * -1.4426950408889634f, ta_ = za * -1.4426950408889634f;
;                         const f32x2 dw = (f32x2){__builtin_amdgcn_exp2f(tw_[0]), __builtin_amdgcn_exp2f(tw_[1])} + 1.f, da = (f32x2){__builtin_amdgcn_exp2f(ta_[0]), __builtin_amdgcn_exp2f(ta_[1])} + 1.f;
;                         const f32x2 sw = (f32x2){__builtin_amdgcn_rcpf(dw[0]), __builtin_amdgcn_rcpf(dw[1])} * -0.8750387749225136f;
;                         dec[pi] = (f32x2){__builtin_amdgcn_exp2f(sw[0]), __builtin_amdgcn_exp2f(sw[1])};
;                         av_[pi] = (f32x2){__builtin_amdgcn_rcpf(da[0]), __builtin_amdgcn_rcpf(da[1])};
;                         kk[pi] = qk[pi] * kkr[pi]; kn2 = kk[pi] * kk[pi] + kn2;
;                         kp[pi] = qk[pi] * (av_[pi] * kar[pi] + omk[pi]);
;                         sb2 = (qr[pi] * kp[pi]) * rkr[pi] + sb2; }
;                     const float kn = red8(kn2[0] + kn2[1]), sbn = red8(sb2[0] + sb2[1]);
;                     const float ninv = -rsqrtf(fmaxf(kn, 1e-12f));
;                     LAS float* dR = OPS + (cn & 1) * SET_F + s_l * 64 + c8;
; #pragma unroll
;                     for (int hf = 0; hf < 2; ++hf) {
;                         const f32x2 na0 = kk[2 * hf] * ninv, na1 = kk[2 * hf + 1] * ninv;
;                         const f32x2 nb0 = na0 * av_[2 * hf], nb1 = na1 * av_[2 * hf + 1];
;                         *(LAS f32x4*)(dR + 4 * hf) = (f32x4){qr[2 * hf][0], qr[2 * hf][1], qr[2 * hf + 1][0], qr[2 * hf + 1][1]};
;                         *(LAS f32x4*)(dR + 2048 + 4 * hf) = (f32x4){dec[2 * hf][0], dec[2 * hf][1], dec[2 * hf + 1][0], dec[2 * hf + 1][1]};
;                         *(LAS f32x4*)(dR + 4096 + 4 * hf) = (f32x4){kp[2 * hf][0], kp[2 * hf][1], kp[2 * hf + 1][0], kp[2 * hf + 1][1]};
	v_pk_add_f32 v[96:97], v[24:25], v[96:97]
	v_pk_fma_f32 v[126:127], v[48:49], v[214:215], v[154:155]
	v_pk_add_f32 v[98:99], v[26:27], v[98:99]
	v_pk_mul_f32 v[126:127], v[126:127], v[100:101]
	v_pk_add_f32 v[100:101], v[34:35], v[128:129]
	v_pk_mul_f32 v[128:129], v[126:127], v[86:87]
	v_pk_mul_f32 v[100:101], v[100:101], s[36:37] op_sel_hi:[1,0]
	v_pk_fma_f32 v[216:217], v[56:57], v[128:129], 0 op_sel_hi:[1,1,0]
	v_exp_f32_e32 v100, v100
	v_exp_f32_e32 v101, v101
	v_pk_mul_f32 v[128:129], v[218:219], v[218:219]
	v_pk_mul_f32 v[224:225], v[36:37], v[230:231]
	v_pk_fma_f32 v[220:221], v[212:213], v[212:213], v[128:129]
	v_pk_add_f32 v[100:101], v[100:101], 1.0 op_sel_hi:[1,0]
	v_pk_mul_f32 v[96:97], v[96:97], s[36:37] op_sel_hi:[1,0]
	v_rcp_f32_e32 v100, v100
	v_rcp_f32_e32 v101, v101
	v_pk_mul_f32 v[98:99], v[98:99], s[36:37] op_sel_hi:[1,0]
	v_pk_add_f32 v[208:209], v[208:209], 1.0 op_sel_hi:[1,0]
	v_exp_f32_e32 v96, v96
	v_pk_fma_f32 v[128:129], v[50:51], v[100:101], v[156:157]
	v_exp_f32_e32 v97, v97
	v_pk_mul_f32 v[128:129], v[128:129], v[94:95]
	v_pk_add_f32 v[94:95], v[28:29], v[206:207]
	v_pk_mul_f32 v[206:207], v[128:129], v[88:89]
	v_pk_mul_f32 v[94:95], v[94:95], s[36:37] op_sel_hi:[1,0]
	v_pk_fma_f32 v[216:217], v[58:59], v[206:207], v[216:217]
	v_exp_f32_e32 v94, v94
	v_exp_f32_e32 v95, v95
	v_exp_f32_e32 v98, v98
	v_exp_f32_e32 v99, v99
	v_pk_mul_f32 v[226:227], v[38:39], v[210:211]
	v_pk_add_f32 v[94:95], v[94:95], 1.0 op_sel_hi:[1,0]
	s_waitcnt lgkmcnt(0)
	v_pk_add_f32 v[202:203], v[20:21], v[202:203]
	v_rcp_f32_e32 v222, v94
	v_rcp_f32_e32 v223, v95
	v_pk_fma_f32 v[94:95], v[224:225], v[224:225], v[220:221]
	v_pk_add_f32 v[204:205], v[22:23], v[204:205]
	v_pk_fma_f32 v[94:95], v[226:227], v[226:227], v[94:95]
	v_pk_fma_f32 v[206:207], v[44:45], v[222:223], v[158:159]
	v_cvt_f32_f16_e32 v92, v242
	v_pk_mul_f32 v[206:207], v[206:207], v[230:231]
	v_cvt_f32_f16_sdwa v93, v242 dst_sel:DWORD dst_unused:UNUSED_PAD src0_sel:WORD_1
	v_pk_mul_f32 v[220:221], v[206:207], v[90:91]
	v_pk_mul_f32 v[202:203], v[202:203], s[36:37] op_sel_hi:[1,0]
	v_pk_fma_f32 v[216:217], v[52:53], v[220:221], v[216:217]
	v_rcp_f32_e32 v220, v208
	v_rcp_f32_e32 v221, v209
	v_pk_mul_f32 v[204:205], v[204:205], s[36:37] op_sel_hi:[1,0]
	v_add_f32_e32 v0, v94, v95
	v_exp_f32_e32 v202, v202
	v_exp_f32_e32 v203, v203
	v_exp_f32_e32 v204, v204
	v_exp_f32_e32 v205, v205
	v_add_f32_dpp v0, v0, v0 quad_perm:[1,0,3,2] row_mask:0xf bank_mask:0xf bound_ctrl:1
	v_pk_add_f32 v[96:97], v[96:97], 1.0 op_sel_hi:[1,0]
	v_pk_add_f32 v[98:99], v[98:99], 1.0 op_sel_hi:[1,0]
	v_pk_fma_f32 v[208:209], v[46:47], v[220:221], v[160:161]
	v_add_f32_dpp v0, v0, v0 quad_perm:[2,3,0,1] row_mask:0xf bank_mask:0xf bound_ctrl:1
	v_rcp_f32_e32 v96, v96
	v_rcp_f32_e32 v97, v97
	v_rcp_f32_e32 v98, v98
	v_rcp_f32_e32 v99, v99
	v_pk_mul_f32 v[208:209], v[208:209], v[210:211]
	v_add_f32_dpp v95, v0, v0 row_half_mirror row_mask:0xf bank_mask:0xf bound_ctrl:1
	v_pk_mul_f32 v[210:211], v[208:209], v[92:93]
	v_max_f32_e32 v95, 0x2b8cbccc, v95
	v_pk_add_f32 v[202:203], v[202:203], 1.0 op_sel_hi:[1,0]
	v_pk_add_f32 v[204:205], v[204:205], 1.0 op_sel_hi:[1,0]
	v_pk_fma_f32 v[210:211], v[54:55], v[210:211], v[216:217]
	v_rsq_f32_e32 v216, v95
	v_rcp_f32_e32 v202, v202
	v_rcp_f32_e32 v203, v203
	v_rcp_f32_e32 v204, v204
	v_rcp_f32_e32 v205, v205
	v_pk_mul_f32 v[96:97], v[96:97], s[38:39] op_sel_hi:[1,0]
	v_pk_mul_f32 v[98:99], v[98:99], s[38:39] op_sel_hi:[1,0]
	v_add3_u32 v95, s15, v175, v144
	v_exp_f32_e32 v96, v96
	v_exp_f32_e32 v97, v97
	v_exp_f32_e32 v98, v98
	v_exp_f32_e32 v99, v99
	v_add_u32_e32 v217, 0x8800, v95
	v_add_f32_e32 v0, v210, v211
	v_pk_mul_f32 v[210:211], v[212:213], v[216:217] op_sel_hi:[1,0] neg_lo:[0,1] neg_hi:[0,1]
	v_pk_mul_f32 v[212:213], v[218:219], v[216:217] op_sel_hi:[1,0] neg_lo:[0,1] neg_hi:[0,1]
	v_pk_mul_f32 v[202:203], v[202:203], s[38:39] op_sel_hi:[1,0]
	v_pk_mul_f32 v[204:205], v[204:205], s[38:39] op_sel_hi:[1,0]
	v_pk_mul_f32 v[100:101], v[212:213], v[100:101]
	s_waitcnt lgkmcnt(0)
	v_exp_f32_e32 v202, v202
	v_exp_f32_e32 v203, v203
	v_exp_f32_e32 v204, v204
	v_exp_f32_e32 v205, v205
	ds_write_b128 v95, v[86:89] offset:34816
	ds_write_b128 v95, v[96:99] offset:43008
	ds_write_b128 v95, v[126:129] offset:51200
	ds_write_b128 v95, v[210:213] offset:59392
	v_pk_mul_f32 v[86:87], v[210:211], v[214:215] neg_lo:[0,1] neg_hi:[0,1]
	v_xor_b32_e32 v88, 0x80000000, v100
	v_xor_b32_e32 v89, 0x80000000, v101
	v_add_f32_dpp v0, v0, v0 quad_perm:[1,0,3,2] row_mask:0xf bank_mask:0xf bound_ctrl:1
	ds_write_b128 v217, v[86:89] offset:32768
	v_pk_mul_f32 v[88:89], v[226:227], v[216:217] op_sel_hi:[1,0] neg_lo:[0,1] neg_hi:[0,1]
	v_add_f32_dpp v0, v0, v0 quad_perm:[2,3,0,1] row_mask:0xf bank_mask:0xf bound_ctrl:1
	v_mov_b32_e32 v94, 0
	v_pk_mul_f32 v[86:87], v[224:225], v[216:217] op_sel_hi:[1,0] neg_lo:[0,1] neg_hi:[0,1]
	v_pk_mul_f32 v[96:97], v[88:89], v[220:221]
	v_mov_b32_dpp v94, v0 row_half_mirror row_mask:0xf bank_mask:0xf
	ds_write_b128 v95, v[90:93] offset:34832
	ds_write_b128 v95, v[202:205] offset:43024
	ds_write_b128 v95, v[206:209] offset:51216
	ds_write_b128 v95, v[86:89] offset:59408
	v_pk_mul_f32 v[86:87], v[86:87], v[222:223] neg_lo:[0,1] neg_hi:[0,1]
	v_xor_b32_e32 v88, 0x80000000, v96
	v_xor_b32_e32 v89, 0x80000000, v97
	ds_write_b128 v217, v[86:89] offset:32784
	s_and_saveexec_b64 s[56:57], s[10:11]
	s_cbranch_execz .LBB0_612
	v_pk_fma_f16 v82, v78, s14, v82
	v_pk_fma_f16 v83, v79, s14, v83
	v_pk_fma_f16 v78, v62, v82, v78
	v_pk_fma_f16 v84, v80, s14, v84
	v_pk_fma_f16 v79, v63, v83, v79
	v_cvt_f32_f16_e32 v82, v78
	v_cvt_f32_f16_sdwa v78, v78 dst_sel:DWORD dst_unused:UNUSED_PAD src0_sel:WORD_1
	s_add_i32 s15, s15, 0x8800
	v_pk_fma_f16 v85, v81, s14, v85
	v_pk_fma_f16 v80, v72, v84, v80
	v_cvt_f32_f16_e32 v83, v79
	v_cvt_f32_f16_sdwa v79, v79 dst_sel:DWORD dst_unused:UNUSED_PAD src0_sel:WORD_1
	v_lshlrev_b32_e32 v86, 2, v169
	v_pk_fma_f16 v81, v73, v85, v81
	v_cvt_f32_f16_e32 v84, v80
	v_cvt_f32_f16_sdwa v80, v80 dst_sel:DWORD dst_unused:UNUSED_PAD src0_sel:WORD_1
	v_add3_u32 v86, s15, v201, v86
	v_cvt_f32_f16_e32 v85, v81
	v_cvt_f32_f16_sdwa v81, v81 dst_sel:DWORD dst_unused:UNUSED_PAD src0_sel:WORD_1
	v_add_u32_e32 v86, 0xa000, v86
	ds_write2_b32 v86, v82, v78 offset1:32
	ds_write2_b32 v86, v83, v79 offset0:64 offset1:96
	ds_write2_b32 v86, v84, v80 offset0:128 offset1:160
	ds_write2_b32 v86, v85, v81 offset0:192 offset1:224
